# attention row-max and P9 relu: canonicalising self-max ops on MFMA results removed
# baseline (speedup 1.0000x reference)
.LBB0_215:
	v_lshl_add_u64 v[150:151], v[148:149], 0, s[58:59]
	ds_read_b128 v[64:67], v181 offset:49152
	ds_read_b128 v[68:71], v181 offset:57344
	v_add_f32_e32 v128, 0, v234
	v_add_f32_e32 v128, v235, v128
	v_add_f32_e32 v128, v236, v128
	s_waitcnt lgkmcnt(1)
	v_mfma_f32_32x32x16_bf16 v[80:95], v[64:67], v[108:111], 0
	v_add_f32_e32 v128, v237, v128
	v_add_f32_e32 v128, v238, v128
	ds_read_b128 v[202:205], v182 offset:49152
	ds_read_b128 v[206:209], v182 offset:57344
	v_add_f32_e32 v128, v239, v128
	v_add_f32_e32 v128, v240, v128
	v_add_f32_e32 v128, v241, v128
	v_add_f32_e32 v128, v242, v128
	s_waitcnt lgkmcnt(2)
	v_mfma_f32_32x32x16_bf16 v[64:79], v[68:71], v[108:111], 0
	v_add_f32_e32 v128, v243, v128
	v_add_f32_e32 v128, v244, v128
	v_add_f32_e32 v128, v245, v128
	v_add_f32_e32 v128, v246, v128
	v_add_f32_e32 v128, v247, v128
	v_add_f32_e32 v128, v252, v128
	v_add_f32_e32 v128, v253, v128
	s_waitcnt lgkmcnt(1)
	v_mfma_f32_32x32x16_bf16 v[80:95], v[202:205], v[104:107], v[80:95]
	v_add_f32_e32 v128, v218, v128
	v_add_f32_e32 v128, v219, v128
	v_add_f32_e32 v128, v220, v128
	v_add_f32_e32 v128, v221, v128
	v_add_f32_e32 v128, v222, v128
	v_add_f32_e32 v128, v223, v128
	v_add_f32_e32 v128, v224, v128
	s_waitcnt lgkmcnt(0)
	v_mfma_f32_32x32x16_bf16 v[64:79], v[206:209], v[104:107], v[64:79]
	ds_read_b128 v[202:205], v183 offset:49152
	ds_read_b128 v[206:209], v183 offset:57344
	v_add_f32_e32 v128, v225, v128
	v_add_f32_e32 v128, v226, v128
	v_add_f32_e32 v128, v227, v128
	v_add_f32_e32 v128, v228, v128
	v_add_f32_e32 v128, v229, v128
	v_add_f32_e32 v128, v230, v128
	s_waitcnt lgkmcnt(1)
	v_mfma_f32_32x32x16_bf16 v[80:95], v[202:205], v[100:103], v[80:95]
	v_add_f32_e32 v128, v231, v128
	v_add_f32_e32 v128, v232, v128
	v_add_f32_e32 v187, v233, v128
	v_mov_b32_e32 v188, v187
	v_lshl_add_u64 v[152:153], v[146:147], 0, s[58:59]
	s_nop 0
	v_permlane32_swap_b32_e32 v187, v188
	s_waitcnt lgkmcnt(0)
	v_mfma_f32_32x32x16_bf16 v[64:79], v[206:209], v[100:103], v[64:79]
	ds_read_b128 v[202:205], v184 offset:49152
	ds_read_b128 v[206:209], v184 offset:57344
	v_cvt_pk_bf16_f32 v128, v234, v235
	v_cvt_pk_bf16_f32 v129, v236, v237
	v_cvt_pk_bf16_f32 v130, v238, v239
	v_cvt_pk_bf16_f32 v131, v240, v241
	v_cvt_pk_bf16_f32 v198, v242, v243
	v_cvt_pk_bf16_f32 v199, v244, v245
	s_waitcnt lgkmcnt(1)
	v_mfma_f32_32x32x16_bf16 v[80:95], v[202:205], v[96:99], v[80:95]
	v_permlane32_swap_b32_e32 v128, v130
	v_cvt_pk_bf16_f32 v200, v246, v247
	v_cvt_pk_bf16_f32 v201, v252, v253
	v_cvt_pk_bf16_f32 v190, v218, v219
	v_cvt_pk_bf16_f32 v191, v220, v221
	v_cvt_pk_bf16_f32 v192, v222, v223
	s_waitcnt lgkmcnt(0)
	v_mfma_f32_32x32x16_bf16 v[64:79], v[206:209], v[96:99], v[64:79]
	v_add_co_u32_e32 v116, vcc, s86, v152
	s_nop 1
	v_addc_co_u32_e32 v117, vcc, 0, v153, vcc
	v_add_co_u32_e32 v120, vcc, s86, v150
	s_nop 1
	v_addc_co_u32_e32 v121, vcc, 0, v151, vcc
	ds_read_b64_tr_b16 v[202:203], v177 offset:0
	ds_read_b64_tr_b16 v[204:205], v177 offset:0x800
	ds_read_b64_tr_b16 v[206:207], v177 offset:0x1000
	ds_read_b64_tr_b16 v[208:209], v177 offset:0x1800
	ds_read_b64_tr_b16 v[210:211], v177 offset:0x2000
	ds_read_b64_tr_b16 v[212:213], v177 offset:0x2800
	ds_read_b64_tr_b16 v[214:215], v177 offset:0x3000
	ds_read_b64_tr_b16 v[216:217], v177 offset:0x3800
	v_cvt_pk_bf16_f32 v193, v224, v225
	v_cvt_pk_bf16_f32 v194, v226, v227
	v_cvt_pk_bf16_f32 v195, v228, v229
	v_cvt_pk_bf16_f32 v196, v230, v231
	v_cvt_pk_bf16_f32 v197, v232, v233
	v_permlane32_swap_b32_e32 v129, v131
	v_permlane32_swap_b32_e32 v198, v200
	v_permlane32_swap_b32_e32 v199, v201
	v_permlane32_swap_b32_e32 v190, v192
	v_permlane32_swap_b32_e32 v191, v193
	v_permlane32_swap_b32_e32 v194, v196
	v_permlane32_swap_b32_e32 v195, v197
	global_load_dwordx4 v[112:115], v[116:117], off offset:1024
	s_nop 0
	global_load_dwordx4 v[116:119], v[116:117], off
	s_nop 0
	global_load_dwordx4 v[124:127], v[120:121], off offset:1024
	s_nop 0
	global_load_dwordx4 v[120:123], v[120:121], off
	s_waitcnt lgkmcnt(0)
	s_nop 0
	v_mfma_f32_32x32x16_bf16 v[0:15], v[128:131], v[202:205], v[0:15]
	ds_read_b64_tr_b16 v[202:203], v177 offset:0x200
	ds_read_b64_tr_b16 v[204:205], v177 offset:0xa00
	v_max_f32_e32 v250, v80, v81
	v_max3_f32 v250, v250, v82, v83
	v_max3_f32 v250, v250, v84, v85
	v_max3_f32 v250, v250, v86, v87
	v_max3_f32 v250, v250, v88, v89
	v_max3_f32 v250, v250, v90, v91
	v_max3_f32 v250, v250, v92, v93
	v_mfma_f32_32x32x16_bf16 v[0:15], v[198:201], v[206:209], v[0:15]
	ds_read_b64_tr_b16 v[206:207], v177 offset:0x1200
	ds_read_b64_tr_b16 v[208:209], v177 offset:0x1a00
	v_max3_f32 v250, v250, v94, v95
	v_max3_f32 v250, v250, v64, v65
	v_max3_f32 v250, v250, v66, v67
	v_max3_f32 v250, v250, v68, v69
	v_max3_f32 v250, v250, v70, v71
	v_max3_f32 v250, v250, v72, v73
	v_max3_f32 v250, v250, v74, v75
	v_max3_f32 v250, v250, v76, v77
	v_max3_f32 v250, v250, v78, v79
	v_mfma_f32_32x32x16_bf16 v[0:15], v[190:193], v[210:213], v[0:15]
	ds_read_b64_tr_b16 v[210:211], v177 offset:0x2200
	ds_read_b64_tr_b16 v[212:213], v177 offset:0x2a00
	v_mov_b32_e32 v251, v250
	s_nop 1
	v_permlane32_swap_b32_e32 v250, v251
	v_max_f32_e32 v250, v250, v251
	v_sub_f32_e32 v251, v250, v186
	v_cmp_ge_f32_e32 vcc, s33, v251
	v_max_f32_e32 v251, v186, v186
	v_max_f32_e32 v250, v251, v250
	v_mfma_f32_32x32x16_bf16 v[0:15], v[194:197], v[214:217], v[0:15]
	ds_read_b64_tr_b16 v[214:215], v177 offset:0x3200
	ds_read_b64_tr_b16 v[216:217], v177 offset:0x3a00
	v_sub_f32_e32 v251, v186, v250
	v_mul_f32_e32 v251, 0x3e38aa3b, v251
	v_exp_f32_e32 v251, v251
	s_cmp_eq_u64 vcc, exec
	s_cselect_b64 s[6:7], -1, 0
	v_cndmask_b32_e64 v186, v250, v186, s[6:7]
	v_mul_f32_e32 v254, 0xbe38aa3b, v186
	s_waitcnt lgkmcnt(0)
	v_mfma_f32_32x32x16_bf16 v[48:63], v[128:131], v[202:205], v[48:63]
	ds_read_b64_tr_b16 v[202:203], v177 offset:0x400
	ds_read_b64_tr_b16 v[204:205], v177 offset:0xc00
	v_fmamk_f32 v80, v80, 0x3e38aa3b, v254
	v_fmamk_f32 v81, v81, 0x3e38aa3b, v254
	v_fmamk_f32 v64, v64, 0x3e38aa3b, v254
	v_fmamk_f32 v65, v65, 0x3e38aa3b, v254
	v_exp_f32_e32 v234, v80
	v_exp_f32_e32 v235, v81
	v_fmamk_f32 v82, v82, 0x3e38aa3b, v254
	v_fmamk_f32 v83, v83, 0x3e38aa3b, v254
	v_mfma_f32_32x32x16_bf16 v[48:63], v[198:201], v[206:209], v[48:63]
	ds_read_b64_tr_b16 v[206:207], v177 offset:0x1400
	ds_read_b64_tr_b16 v[208:209], v177 offset:0x1c00
	v_exp_f32_e32 v218, v64
	v_exp_f32_e32 v219, v65
	v_fmamk_f32 v66, v66, 0x3e38aa3b, v254
	v_fmamk_f32 v67, v67, 0x3e38aa3b, v254
	v_exp_f32_e32 v236, v82
	v_mfma_f32_32x32x16_bf16 v[48:63], v[190:193], v[210:213], v[48:63]
	ds_read_b64_tr_b16 v[210:211], v177 offset:0x2400
	ds_read_b64_tr_b16 v[212:213], v177 offset:0x2c00
	v_exp_f32_e32 v237, v83
	v_fmamk_f32 v84, v84, 0x3e38aa3b, v254
	v_fmamk_f32 v85, v85, 0x3e38aa3b, v254
	v_exp_f32_e32 v220, v66
	v_exp_f32_e32 v221, v67
	v_mfma_f32_32x32x16_bf16 v[48:63], v[194:197], v[214:217], v[48:63]
	ds_read_b64_tr_b16 v[214:215], v177 offset:0x3400
	ds_read_b64_tr_b16 v[216:217], v177 offset:0x3c00
	v_fmamk_f32 v68, v68, 0x3e38aa3b, v254
	v_fmamk_f32 v69, v69, 0x3e38aa3b, v254
	v_exp_f32_e32 v238, v84
	v_exp_f32_e32 v239, v85
	v_fmamk_f32 v86, v86, 0x3e38aa3b, v254
	v_fmamk_f32 v87, v87, 0x3e38aa3b, v254
	s_waitcnt lgkmcnt(0)
	v_mfma_f32_32x32x16_bf16 v[32:47], v[128:131], v[202:205], v[32:47]
	ds_read_b64_tr_b16 v[202:203], v177 offset:0x600
	ds_read_b64_tr_b16 v[204:205], v177 offset:0xe00
	v_exp_f32_e32 v222, v68
	v_exp_f32_e32 v223, v69
	v_fmamk_f32 v70, v70, 0x3e38aa3b, v254
	v_fmamk_f32 v71, v71, 0x3e38aa3b, v254
	v_exp_f32_e32 v240, v86
	v_mfma_f32_32x32x16_bf16 v[32:47], v[198:201], v[206:209], v[32:47]
	ds_read_b64_tr_b16 v[206:207], v177 offset:0x1600
	ds_read_b64_tr_b16 v[208:209], v177 offset:0x1e00
	v_exp_f32_e32 v241, v87
	v_fmamk_f32 v88, v88, 0x3e38aa3b, v254
	v_fmamk_f32 v89, v89, 0x3e38aa3b, v254
	v_exp_f32_e32 v224, v70
	v_exp_f32_e32 v225, v71
	v_mfma_f32_32x32x16_bf16 v[32:47], v[190:193], v[210:213], v[32:47]
	ds_read_b64_tr_b16 v[210:211], v177 offset:0x2600
	ds_read_b64_tr_b16 v[212:213], v177 offset:0x2e00
	v_fmamk_f32 v72, v72, 0x3e38aa3b, v254
	v_fmamk_f32 v73, v73, 0x3e38aa3b, v254
	v_exp_f32_e32 v242, v88
	v_exp_f32_e32 v243, v89
	v_fmamk_f32 v90, v90, 0x3e38aa3b, v254
	v_fmamk_f32 v91, v91, 0x3e38aa3b, v254
	v_mfma_f32_32x32x16_bf16 v[32:47], v[194:197], v[214:217], v[32:47]
	ds_read_b64_tr_b16 v[214:215], v177 offset:0x3600
	ds_read_b64_tr_b16 v[216:217], v177 offset:0x3e00
	v_exp_f32_e32 v226, v72
	v_exp_f32_e32 v227, v73
	v_fmamk_f32 v74, v74, 0x3e38aa3b, v254
	v_fmamk_f32 v75, v75, 0x3e38aa3b, v254
	v_exp_f32_e32 v244, v90
	s_waitcnt lgkmcnt(0)
	v_mfma_f32_32x32x16_bf16 v[16:31], v[128:131], v[202:205], v[16:31]
	v_exp_f32_e32 v245, v91
	v_fmamk_f32 v92, v92, 0x3e38aa3b, v254
	v_fmamk_f32 v93, v93, 0x3e38aa3b, v254
	v_exp_f32_e32 v228, v74
	v_exp_f32_e32 v229, v75
	v_mfma_f32_32x32x16_bf16 v[16:31], v[198:201], v[206:209], v[16:31]
	v_fmamk_f32 v76, v76, 0x3e38aa3b, v254
	v_fmamk_f32 v77, v77, 0x3e38aa3b, v254
	v_exp_f32_e32 v246, v92
	v_exp_f32_e32 v247, v93
	v_fmamk_f32 v94, v94, 0x3e38aa3b, v254
	v_fmamk_f32 v95, v95, 0x3e38aa3b, v254
	v_mfma_f32_32x32x16_bf16 v[16:31], v[190:193], v[210:213], v[16:31]
	v_exp_f32_e32 v230, v76
	v_exp_f32_e32 v231, v77
	v_fmamk_f32 v78, v78, 0x3e38aa3b, v254
	v_fmamk_f32 v79, v79, 0x3e38aa3b, v254
	v_exp_f32_e32 v252, v94
	v_mfma_f32_32x32x16_bf16 v[16:31], v[194:197], v[214:217], v[16:31]
	v_exp_f32_e32 v253, v95
	s_nop 0
	v_exp_f32_e32 v232, v78
	v_exp_f32_e32 v233, v79
	s_barrier
	s_waitcnt vmcnt(0)
	v_cndmask_b32_e64 v202, v251, 1.0, s[6:7]
	v_cmp_gt_f32_e32 vcc, 1.0, v202
	s_waitcnt vmcnt(3)
	ds_write_b128 v134, v[112:115]
	s_waitcnt vmcnt(1)
	ds_write_b128 v145, v[124:127]
	ds_write_b128 v175, v[116:119] offset:32768
	s_waitcnt vmcnt(0)
	ds_write_b128 v180, v[120:123] offset:32768
	s_cbranch_vccz .LBB0_219
	s_and_saveexec_b64 s[60:61], s[4:5]
	ds_write_b32 v176, v202 offset:128
	s_or_b64 exec, exec, s[60:61]
	s_waitcnt lgkmcnt(0)
	v_add_u32_e32 v124, v174, v144
	ds_read_b128 v[112:115], v124 offset:224
	ds_read_b128 v[116:119], v124 offset:192
	ds_read_b128 v[120:123], v124 offset:160
	ds_read_b128 v[124:127], v124 offset:128
	s_waitcnt lgkmcnt(3)
	v_pk_mul_f32 v[12:13], v[12:13], v[112:113]
	s_waitcnt lgkmcnt(2)
	v_pk_mul_f32 v[8:9], v[8:9], v[116:117]
	s_waitcnt lgkmcnt(1)
	v_pk_mul_f32 v[4:5], v[4:5], v[120:121]
	v_pk_mul_f32 v[14:15], v[14:15], v[114:115]
	v_pk_mul_f32 v[10:11], v[10:11], v[118:119]
	v_pk_mul_f32 v[6:7], v[6:7], v[122:123]
	s_waitcnt lgkmcnt(0)
	v_pk_mul_f32 v[2:3], v[2:3], v[126:127]
	v_pk_mul_f32 v[0:1], v[0:1], v[124:125]
	v_pk_mul_f32 v[60:61], v[60:61], v[112:113]
	v_pk_mul_f32 v[56:57], v[56:57], v[116:117]
	v_pk_mul_f32 v[52:53], v[52:53], v[120:121]
	v_pk_mul_f32 v[62:63], v[62:63], v[114:115]
	v_pk_mul_f32 v[58:59], v[58:59], v[118:119]
	v_pk_mul_f32 v[54:55], v[54:55], v[122:123]
	v_pk_mul_f32 v[50:51], v[50:51], v[126:127]
	v_pk_mul_f32 v[48:49], v[48:49], v[124:125]
	v_pk_mul_f32 v[44:45], v[44:45], v[112:113]
	v_pk_mul_f32 v[40:41], v[40:41], v[116:117]
	v_pk_mul_f32 v[36:37], v[36:37], v[120:121]
	v_pk_mul_f32 v[46:47], v[46:47], v[114:115]
	v_pk_mul_f32 v[42:43], v[42:43], v[118:119]
	v_pk_mul_f32 v[38:39], v[38:39], v[122:123]
	v_pk_mul_f32 v[34:35], v[34:35], v[126:127]
	v_pk_mul_f32 v[32:33], v[32:33], v[124:125]
	v_pk_mul_f32 v[28:29], v[28:29], v[112:113]
	v_pk_mul_f32 v[24:25], v[24:25], v[116:117]
	v_pk_mul_f32 v[20:21], v[20:21], v[120:121]
	v_pk_mul_f32 v[30:31], v[30:31], v[114:115]
	v_pk_mul_f32 v[26:27], v[26:27], v[118:119]
	v_pk_mul_f32 v[22:23], v[22:23], v[122:123]
	v_pk_mul_f32 v[18:19], v[18:19], v[126:127]
	v_pk_mul_f32 v[16:17], v[16:17], v[124:125]
.LBB0_219:
	s_waitcnt lgkmcnt(0)
	s_barrier
	ds_read_b128 v[64:67], v181 offset:32768
	ds_read_b128 v[68:71], v181 offset:40960
	v_add_f32_e32 v201, 0, v234
	v_add_f32_e32 v201, v235, v201
	v_add_f32_e32 v201, v236, v201
	s_waitcnt lgkmcnt(1)
	v_mfma_f32_32x32x16_bf16 v[80:95], v[64:67], v[108:111], 0
	v_add_f32_e32 v201, v237, v201
	v_add_f32_e32 v201, v238, v201
	ds_read_b128 v[204:207], v182 offset:32768
	ds_read_b128 v[208:211], v182 offset:40960
	v_add_f32_e32 v201, v239, v201
	v_add_f32_e32 v201, v240, v201
	v_add_f32_e32 v201, v241, v201
	v_add_f32_e32 v201, v242, v201
	s_waitcnt lgkmcnt(2)
	v_mfma_f32_32x32x16_bf16 v[64:79], v[68:71], v[108:111], 0
	v_add_f32_e32 v201, v243, v201
	v_add_f32_e32 v201, v244, v201
	v_add_f32_e32 v201, v245, v201
	v_add_f32_e32 v201, v246, v201
	v_add_f32_e32 v201, v247, v201
	v_add_f32_e32 v201, v252, v201
	v_add_f32_e32 v201, v253, v201
	s_waitcnt lgkmcnt(1)
	v_mfma_f32_32x32x16_bf16 v[80:95], v[204:207], v[104:107], v[80:95]
	v_add_f32_e32 v201, v218, v201
	v_add_f32_e32 v201, v219, v201
	v_add_f32_e32 v201, v220, v201
	v_add_f32_e32 v201, v221, v201
	v_add_f32_e32 v201, v222, v201
	v_add_f32_e32 v201, v223, v201
	v_add_f32_e32 v201, v224, v201
	s_waitcnt lgkmcnt(0)
	v_mfma_f32_32x32x16_bf16 v[64:79], v[208:211], v[104:107], v[64:79]
	ds_read_b128 v[204:207], v183 offset:32768
	ds_read_b128 v[208:211], v183 offset:40960
	v_add_f32_e32 v201, v225, v201
	v_add_f32_e32 v201, v226, v201
	v_add_f32_e32 v201, v227, v201
	v_add_f32_e32 v201, v228, v201
	v_add_f32_e32 v201, v229, v201
	v_add_f32_e32 v201, v230, v201
	s_waitcnt lgkmcnt(1)
	v_mfma_f32_32x32x16_bf16 v[80:95], v[204:207], v[100:103], v[80:95]
	v_add_f32_e32 v201, v231, v201
	v_add_f32_e32 v201, v232, v201
	v_add_f32_e32 v203, v233, v201
	s_waitcnt lgkmcnt(0)
	v_mfma_f32_32x32x16_bf16 v[64:79], v[208:211], v[100:103], v[64:79]
	ds_read_b128 v[204:207], v184 offset:32768
	ds_read_b128 v[208:211], v184 offset:40960
	v_cvt_pk_bf16_f32 v128, v234, v235
	v_cvt_pk_bf16_f32 v129, v236, v237
	v_cvt_pk_bf16_f32 v130, v238, v239
	v_cvt_pk_bf16_f32 v131, v240, v241
	v_cvt_pk_bf16_f32 v198, v242, v243
	v_cvt_pk_bf16_f32 v199, v244, v245
	s_waitcnt lgkmcnt(1)
	v_mfma_f32_32x32x16_bf16 v[80:95], v[204:207], v[96:99], v[80:95]
	v_mov_b32_e32 v204, v203
	s_nop 1
	v_permlane32_swap_b32_e32 v203, v204
	v_permlane32_swap_b32_e32 v128, v130
	v_permlane32_swap_b32_e32 v129, v131
	s_waitcnt lgkmcnt(0)
	v_mfma_f32_32x32x16_bf16 v[64:79], v[208:211], v[96:99], v[64:79]
	v_add_co_u32_e32 v116, vcc, s78, v152
	s_nop 1
	v_addc_co_u32_e32 v117, vcc, 0, v153, vcc
	v_add_co_u32_e32 v120, vcc, s78, v150
	s_nop 1
	v_addc_co_u32_e32 v121, vcc, 0, v151, vcc
	ds_read_b64_tr_b16 v[150:151], v179 offset:0
	ds_read_b64_tr_b16 v[152:153], v179 offset:0x800
	ds_read_b64_tr_b16 v[206:207], v179 offset:0x1000
	ds_read_b64_tr_b16 v[208:209], v179 offset:0x1800
	ds_read_b64_tr_b16 v[210:211], v179 offset:0x2000
	ds_read_b64_tr_b16 v[212:213], v179 offset:0x2800
	ds_read_b64_tr_b16 v[214:215], v179 offset:0x3000
	ds_read_b64_tr_b16 v[216:217], v179 offset:0x3800
	v_cvt_pk_bf16_f32 v200, v246, v247
	v_cvt_pk_bf16_f32 v201, v252, v253
	v_cvt_pk_bf16_f32 v190, v218, v219
	v_cvt_pk_bf16_f32 v191, v220, v221
	v_cvt_pk_bf16_f32 v192, v222, v223
	v_cvt_pk_bf16_f32 v193, v224, v225
	v_cvt_pk_bf16_f32 v194, v226, v227
	v_cvt_pk_bf16_f32 v195, v228, v229
	v_cvt_pk_bf16_f32 v196, v230, v231
	v_cvt_pk_bf16_f32 v197, v232, v233
	s_nop 0
	v_permlane32_swap_b32_e32 v198, v200
	v_permlane32_swap_b32_e32 v199, v201
	v_permlane32_swap_b32_e32 v190, v192
	v_permlane32_swap_b32_e32 v191, v193
	v_permlane32_swap_b32_e32 v194, v196
	v_permlane32_swap_b32_e32 v195, v197
	global_load_dwordx4 v[112:115], v[116:117], off offset:1024
	s_nop 0
	global_load_dwordx4 v[116:119], v[116:117], off
	s_nop 0
	global_load_dwordx4 v[124:127], v[120:121], off offset:1024
	s_nop 0
	global_load_dwordx4 v[120:123], v[120:121], off
	s_waitcnt lgkmcnt(0)
	s_nop 0
	v_mfma_f32_32x32x16_bf16 v[0:15], v[128:131], v[150:153], v[0:15]
	ds_read_b64_tr_b16 v[150:151], v179 offset:0x200
	ds_read_b64_tr_b16 v[152:153], v179 offset:0xa00
	v_max_f32_e32 v250, v80, v81
	v_max3_f32 v250, v250, v82, v83
	v_max3_f32 v250, v250, v84, v85
	v_max3_f32 v250, v250, v86, v87
	v_max3_f32 v250, v250, v88, v89
	v_max3_f32 v250, v250, v90, v91
	v_max3_f32 v250, v250, v92, v93
	v_mfma_f32_32x32x16_bf16 v[0:15], v[198:201], v[206:209], v[0:15]
	ds_read_b64_tr_b16 v[206:207], v179 offset:0x1200
	ds_read_b64_tr_b16 v[208:209], v179 offset:0x1a00
	v_max3_f32 v250, v250, v94, v95
	v_max3_f32 v250, v250, v64, v65
	v_max3_f32 v250, v250, v66, v67
	v_max3_f32 v250, v250, v68, v69
	v_max3_f32 v250, v250, v70, v71
	v_max3_f32 v250, v250, v72, v73
	v_max3_f32 v250, v250, v74, v75
	v_max3_f32 v250, v250, v76, v77
	v_max3_f32 v250, v250, v78, v79
	v_mfma_f32_32x32x16_bf16 v[0:15], v[190:193], v[210:213], v[0:15]
	ds_read_b64_tr_b16 v[210:211], v179 offset:0x2200
	ds_read_b64_tr_b16 v[212:213], v179 offset:0x2a00
	v_mov_b32_e32 v251, v250
	s_nop 1
	v_permlane32_swap_b32_e32 v250, v251
	v_max_f32_e32 v250, v250, v251
	v_sub_f32_e32 v251, v250, v186
	v_cmp_ge_f32_e32 vcc, s33, v251
	v_max_f32_e32 v251, v186, v186
	v_max_f32_e32 v251, v251, v250
	v_mfma_f32_32x32x16_bf16 v[0:15], v[194:197], v[214:217], v[0:15]
	ds_read_b64_tr_b16 v[214:215], v179 offset:0x3200
	ds_read_b64_tr_b16 v[216:217], v179 offset:0x3a00
	v_sub_f32_e32 v250, v186, v251
	v_mul_f32_e32 v250, 0x3e38aa3b, v250
	v_exp_f32_e32 v250, v250
	s_cmp_eq_u64 vcc, exec
	s_cselect_b64 s[6:7], -1, 0
	v_cndmask_b32_e64 v186, v251, v186, s[6:7]
	v_mul_f32_e32 v254, 0xbe38aa3b, v186
	s_waitcnt lgkmcnt(0)
	v_mfma_f32_32x32x16_bf16 v[48:63], v[128:131], v[150:153], v[48:63]
	ds_read_b64_tr_b16 v[150:151], v179 offset:0x400
	ds_read_b64_tr_b16 v[152:153], v179 offset:0xc00
	v_fmamk_f32 v80, v80, 0x3e38aa3b, v254
	v_fmamk_f32 v81, v81, 0x3e38aa3b, v254
	v_fmamk_f32 v64, v64, 0x3e38aa3b, v254
	v_fmamk_f32 v65, v65, 0x3e38aa3b, v254
	v_exp_f32_e32 v234, v80
	v_exp_f32_e32 v235, v81
	v_fmamk_f32 v82, v82, 0x3e38aa3b, v254
	v_fmamk_f32 v83, v83, 0x3e38aa3b, v254
	v_mfma_f32_32x32x16_bf16 v[48:63], v[198:201], v[206:209], v[48:63]
	ds_read_b64_tr_b16 v[206:207], v179 offset:0x1400
	ds_read_b64_tr_b16 v[208:209], v179 offset:0x1c00
	v_exp_f32_e32 v218, v64
	v_exp_f32_e32 v219, v65
	v_fmamk_f32 v66, v66, 0x3e38aa3b, v254
	v_fmamk_f32 v67, v67, 0x3e38aa3b, v254
	v_exp_f32_e32 v236, v82
	v_mfma_f32_32x32x16_bf16 v[48:63], v[190:193], v[210:213], v[48:63]
	ds_read_b64_tr_b16 v[210:211], v179 offset:0x2400
	ds_read_b64_tr_b16 v[212:213], v179 offset:0x2c00
	v_exp_f32_e32 v237, v83
	v_fmamk_f32 v84, v84, 0x3e38aa3b, v254
	v_fmamk_f32 v85, v85, 0x3e38aa3b, v254
	v_exp_f32_e32 v220, v66
	v_exp_f32_e32 v221, v67
	v_mfma_f32_32x32x16_bf16 v[48:63], v[194:197], v[214:217], v[48:63]
	ds_read_b64_tr_b16 v[214:215], v179 offset:0x3400
	ds_read_b64_tr_b16 v[216:217], v179 offset:0x3c00
	v_fmamk_f32 v68, v68, 0x3e38aa3b, v254
	v_fmamk_f32 v69, v69, 0x3e38aa3b, v254
	v_exp_f32_e32 v238, v84
	v_exp_f32_e32 v239, v85
	v_fmamk_f32 v86, v86, 0x3e38aa3b, v254
	v_fmamk_f32 v87, v87, 0x3e38aa3b, v254
	s_waitcnt lgkmcnt(0)
	v_mfma_f32_32x32x16_bf16 v[32:47], v[128:131], v[150:153], v[32:47]
	ds_read_b64_tr_b16 v[150:151], v179 offset:0x600
	ds_read_b64_tr_b16 v[152:153], v179 offset:0xe00
	v_exp_f32_e32 v222, v68
	v_exp_f32_e32 v223, v69
	v_fmamk_f32 v70, v70, 0x3e38aa3b, v254
	v_fmamk_f32 v71, v71, 0x3e38aa3b, v254
	v_exp_f32_e32 v240, v86
	v_mfma_f32_32x32x16_bf16 v[32:47], v[198:201], v[206:209], v[32:47]
	ds_read_b64_tr_b16 v[206:207], v179 offset:0x1600
	ds_read_b64_tr_b16 v[208:209], v179 offset:0x1e00
	v_exp_f32_e32 v241, v87
	v_fmamk_f32 v88, v88, 0x3e38aa3b, v254
	v_fmamk_f32 v89, v89, 0x3e38aa3b, v254
	v_exp_f32_e32 v224, v70
	v_exp_f32_e32 v225, v71
	v_mfma_f32_32x32x16_bf16 v[32:47], v[190:193], v[210:213], v[32:47]
	ds_read_b64_tr_b16 v[210:211], v179 offset:0x2600
	ds_read_b64_tr_b16 v[212:213], v179 offset:0x2e00
	v_fmamk_f32 v72, v72, 0x3e38aa3b, v254
	v_fmamk_f32 v73, v73, 0x3e38aa3b, v254
	v_exp_f32_e32 v242, v88
	v_exp_f32_e32 v243, v89
	v_fmamk_f32 v90, v90, 0x3e38aa3b, v254
	v_fmamk_f32 v91, v91, 0x3e38aa3b, v254
	v_mfma_f32_32x32x16_bf16 v[32:47], v[194:197], v[214:217], v[32:47]
	ds_read_b64_tr_b16 v[214:215], v179 offset:0x3600
	ds_read_b64_tr_b16 v[216:217], v179 offset:0x3e00
	v_exp_f32_e32 v226, v72
	v_exp_f32_e32 v227, v73
	v_fmamk_f32 v74, v74, 0x3e38aa3b, v254
	v_fmamk_f32 v75, v75, 0x3e38aa3b, v254
	v_exp_f32_e32 v244, v90
	s_waitcnt lgkmcnt(0)
	v_mfma_f32_32x32x16_bf16 v[16:31], v[128:131], v[150:153], v[16:31]
	v_exp_f32_e32 v245, v91
	v_fmamk_f32 v92, v92, 0x3e38aa3b, v254
	v_fmamk_f32 v93, v93, 0x3e38aa3b, v254
	v_exp_f32_e32 v228, v74
	v_exp_f32_e32 v229, v75
	v_mfma_f32_32x32x16_bf16 v[16:31], v[198:201], v[206:209], v[16:31]
	v_fmamk_f32 v76, v76, 0x3e38aa3b, v254
	v_fmamk_f32 v77, v77, 0x3e38aa3b, v254
	v_exp_f32_e32 v246, v92
	v_exp_f32_e32 v247, v93
	v_fmamk_f32 v94, v94, 0x3e38aa3b, v254
	v_fmamk_f32 v95, v95, 0x3e38aa3b, v254
	v_mfma_f32_32x32x16_bf16 v[16:31], v[190:193], v[210:213], v[16:31]
	v_exp_f32_e32 v230, v76
	v_exp_f32_e32 v231, v77
	v_fmamk_f32 v78, v78, 0x3e38aa3b, v254
	v_fmamk_f32 v79, v79, 0x3e38aa3b, v254
	v_exp_f32_e32 v252, v94
	v_mfma_f32_32x32x16_bf16 v[16:31], v[194:197], v[214:217], v[16:31]
	v_exp_f32_e32 v253, v95
	s_nop 0
	v_exp_f32_e32 v232, v78
	v_exp_f32_e32 v233, v79
	s_barrier
	s_waitcnt vmcnt(0)
	v_cndmask_b32_e64 v128, v250, 1.0, s[6:7]
	v_cmp_gt_f32_e32 vcc, 1.0, v128
	s_waitcnt vmcnt(3)
	ds_write_b128 v134, v[112:115] offset:16384
	s_waitcnt vmcnt(1)
	ds_write_b128 v145, v[124:127] offset:16384
	ds_write_b128 v175, v[116:119] offset:49152
	s_waitcnt vmcnt(0)
	ds_write_b128 v180, v[120:123] offset:49152
	s_cbranch_vccz .LBB0_223
	s_and_saveexec_b64 s[60:61], s[4:5]
	ds_write_b32 v176, v128 offset:128
	s_or_b64 exec, exec, s[60:61]
	s_waitcnt lgkmcnt(0)
	v_add_u32_e32 v124, v174, v144
	ds_read_b128 v[112:115], v124 offset:224
	ds_read_b128 v[116:119], v124 offset:192
	ds_read_b128 v[120:123], v124 offset:160
	ds_read_b128 v[124:127], v124 offset:128
	s_waitcnt lgkmcnt(3)
	v_pk_mul_f32 v[12:13], v[12:13], v[112:113]
	s_waitcnt lgkmcnt(2)
	v_pk_mul_f32 v[8:9], v[8:9], v[116:117]
	s_waitcnt lgkmcnt(1)
	v_pk_mul_f32 v[4:5], v[4:5], v[120:121]
	v_pk_mul_f32 v[14:15], v[14:15], v[114:115]
	v_pk_mul_f32 v[10:11], v[10:11], v[118:119]
	v_pk_mul_f32 v[6:7], v[6:7], v[122:123]
	s_waitcnt lgkmcnt(0)
	v_pk_mul_f32 v[2:3], v[2:3], v[126:127]
	v_pk_mul_f32 v[0:1], v[0:1], v[124:125]
	v_pk_mul_f32 v[60:61], v[60:61], v[112:113]
	v_pk_mul_f32 v[56:57], v[56:57], v[116:117]
	v_pk_mul_f32 v[52:53], v[52:53], v[120:121]
	v_pk_mul_f32 v[62:63], v[62:63], v[114:115]
	v_pk_mul_f32 v[58:59], v[58:59], v[118:119]
	v_pk_mul_f32 v[54:55], v[54:55], v[122:123]
	v_pk_mul_f32 v[50:51], v[50:51], v[126:127]
	v_pk_mul_f32 v[48:49], v[48:49], v[124:125]
	v_pk_mul_f32 v[44:45], v[44:45], v[112:113]
	v_pk_mul_f32 v[40:41], v[40:41], v[116:117]
	v_pk_mul_f32 v[36:37], v[36:37], v[120:121]
	v_pk_mul_f32 v[46:47], v[46:47], v[114:115]
	v_pk_mul_f32 v[42:43], v[42:43], v[118:119]
	v_pk_mul_f32 v[38:39], v[38:39], v[122:123]
	v_pk_mul_f32 v[34:35], v[34:35], v[126:127]
	v_pk_mul_f32 v[32:33], v[32:33], v[124:125]
	v_pk_mul_f32 v[28:29], v[28:29], v[112:113]
	v_pk_mul_f32 v[24:25], v[24:25], v[116:117]
	v_pk_mul_f32 v[20:21], v[20:21], v[120:121]
	v_pk_mul_f32 v[30:31], v[30:31], v[114:115]
	v_pk_mul_f32 v[26:27], v[26:27], v[118:119]
	v_pk_mul_f32 v[22:23], v[22:23], v[122:123]
	v_pk_mul_f32 v[18:19], v[18:19], v[126:127]
	v_pk_mul_f32 v[16:17], v[16:17], v[124:125]

.LBB0_1124:
	v_and_b32_e32 v254, 1, v149
	v_mul_u32_u24_e32 v254, 24, v254
	v_mov_b32_e32 v255, 0
	v_or_b32_e32 v128, s6, v142
	v_add_u32_e32 v128, v128, v134
	v_or_b32_e32 v130, s7, v143
	v_mov_b64_e32 v[138:139], v[132:133]
	v_ashrrev_i32_e32 v129, 31, v128
	v_ashrrev_i32_e32 v131, 31, v130
	v_lshlrev_b64 v[140:141], 13, v[128:129]
	v_lshl_add_u64 v[138:139], v[138:139], 0, v[140:141]
	v_lshlrev_b64 v[130:131], 1, v[130:131]
	v_lshl_add_u64 v[138:139], v[138:139], 0, v[130:131]
	v_lshlrev_b32_e32 v134, 3, v149
	v_max_f32_e32 v124, 0, v124
	v_max_f32_e32 v125, 0, v125
	v_max_f32_e32 v126, 0, v126
	v_lshl_add_u64 v[138:139], v[138:139], 0, v[134:135]
	v_max_f32_e32 v127, 0, v127
	v_mul_f32_e32 v124, v124, v124
	v_mul_f32_e32 v125, v125, v125
	v_mul_f32_e32 v126, v126, v126
	v_mul_f32_e32 v127, v127, v127
	v_cvt_pk_bf16_f32 v124, v124, v125
	v_cvt_pk_bf16_f32 v125, v126, v127
	v_max_f32_e32 v120, 0, v120
	v_max_f32_e32 v121, 0, v121
	v_max_f32_e32 v116, 0, v116
	v_max_f32_e32 v117, 0, v117
	v_max_f32_e32 v112, 0, v112
	v_max_f32_e32 v113, 0, v113
	v_max_f32_e32 v108, 0, v108
	v_max_f32_e32 v109, 0, v109
	v_max_f32_e32 v104, 0, v104
	v_max_f32_e32 v105, 0, v105
	v_max_f32_e32 v100, 0, v100
	v_max_f32_e32 v101, 0, v101
	v_max_f32_e32 v96, 0, v96
	v_lshl_add_u64 v[140:141], v[138:139], 0, s[22:23]
	v_lshl_add_u64 v[140:141], v[140:141], 0, v[254:255]
	v_max_f32_e32 v122, 0, v122
	v_max_f32_e32 v123, 0, v123
	v_mul_f32_e32 v120, v120, v120
	v_mul_f32_e32 v121, v121, v121
	v_max_f32_e32 v118, 0, v118
	v_max_f32_e32 v119, 0, v119
	v_mul_f32_e32 v116, v116, v116
	v_mul_f32_e32 v117, v117, v117
	v_max_f32_e32 v114, 0, v114
	v_max_f32_e32 v115, 0, v115
	v_mul_f32_e32 v112, v112, v112
	v_mul_f32_e32 v113, v113, v113
	v_max_f32_e32 v110, 0, v110
	v_max_f32_e32 v111, 0, v111
	v_mul_f32_e32 v108, v108, v108
	v_mul_f32_e32 v109, v109, v109
	v_max_f32_e32 v106, 0, v106
	v_max_f32_e32 v107, 0, v107
	v_mul_f32_e32 v104, v104, v104
	v_mul_f32_e32 v105, v105, v105
	v_max_f32_e32 v102, 0, v102
	v_max_f32_e32 v103, 0, v103
	v_mul_f32_e32 v100, v100, v100
	v_mul_f32_e32 v101, v101, v101
	v_max_f32_e32 v97, 0, v97
	v_mul_f32_e32 v96, v96, v96
	v_mul_f32_e32 v122, v122, v122
	v_mul_f32_e32 v123, v123, v123
	v_cvt_pk_bf16_f32 v126, v120, v121
	v_cvt_pk_bf16_f32 v127, v122, v123
	s_nop 1
	v_permlane16_swap_b32_e32 v124, v126
	v_permlane16_swap_b32_e32 v125, v127
	global_store_dwordx4 v[140:141], v[124:127], off
	s_nop 1
	v_mul_f32_e32 v118, v118, v118
	v_mul_f32_e32 v119, v119, v119
	v_cvt_pk_bf16_f32 v116, v116, v117
	v_cvt_pk_bf16_f32 v117, v118, v119
	v_mul_f32_e32 v114, v114, v114
	v_mul_f32_e32 v115, v115, v115
	v_cvt_pk_bf16_f32 v118, v112, v113
	v_cvt_pk_bf16_f32 v119, v114, v115
	s_nop 1
	v_permlane16_swap_b32_e32 v116, v118
	v_permlane16_swap_b32_e32 v117, v119
	global_store_dwordx4 v[140:141], v[116:119], off offset:64
	s_nop 1
	v_mul_f32_e32 v110, v110, v110
	v_mul_f32_e32 v111, v111, v111
	v_cvt_pk_bf16_f32 v108, v108, v109
	v_cvt_pk_bf16_f32 v109, v110, v111
	v_mul_f32_e32 v106, v106, v106
	v_mul_f32_e32 v107, v107, v107
	v_cvt_pk_bf16_f32 v110, v104, v105
	v_cvt_pk_bf16_f32 v111, v106, v107
	s_nop 1
	v_permlane16_swap_b32_e32 v108, v110
	v_permlane16_swap_b32_e32 v109, v111
	global_store_dwordx4 v[140:141], v[108:111], off offset:128
	s_nop 1
	v_mul_f32_e32 v102, v102, v102
	v_mul_f32_e32 v103, v103, v103
	v_cvt_pk_bf16_f32 v100, v100, v101
	v_cvt_pk_bf16_f32 v101, v102, v103
	v_max_f32_e32 v98, 0, v98
	v_max_f32_e32 v99, 0, v99
	v_mul_f32_e32 v97, v97, v97
	v_cvt_pk_bf16_f32 v102, v96, v97
	v_mul_f32_e32 v98, v98, v98
	v_mul_f32_e32 v99, v99, v99
	v_cvt_pk_bf16_f32 v103, v98, v99
	s_nop 1
	v_permlane16_swap_b32_e32 v100, v102
	v_permlane16_swap_b32_e32 v101, v103
	global_store_dwordx4 v[140:141], v[100:103], off offset:192
	s_nop 1
	v_or_b32_e32 v96, 16, v128
	v_ashrrev_i32_e32 v97, 31, v96
	v_mov_b64_e32 v[98:99], v[132:133]
	v_lshlrev_b64 v[96:97], 13, v[96:97]
	v_lshl_add_u64 v[96:97], v[98:99], 0, v[96:97]
	v_lshl_add_u64 v[96:97], v[96:97], 0, v[130:131]
	v_max_f32_e32 v92, 0, v92
	v_max_f32_e32 v93, 0, v93
	v_max_f32_e32 v94, 0, v94
	v_lshl_add_u64 v[96:97], v[96:97], 0, v[134:135]
	v_max_f32_e32 v95, 0, v95
	v_mul_f32_e32 v92, v92, v92
	v_mul_f32_e32 v93, v93, v93
	v_mul_f32_e32 v94, v94, v94
	v_mul_f32_e32 v95, v95, v95
	v_cvt_pk_bf16_f32 v92, v92, v93
	v_cvt_pk_bf16_f32 v93, v94, v95
	v_max_f32_e32 v88, 0, v88
	v_max_f32_e32 v89, 0, v89
	v_max_f32_e32 v84, 0, v84
	v_max_f32_e32 v85, 0, v85
	v_max_f32_e32 v80, 0, v80
	v_max_f32_e32 v81, 0, v81
	v_max_f32_e32 v76, 0, v76
	v_max_f32_e32 v77, 0, v77
	v_max_f32_e32 v72, 0, v72
	v_max_f32_e32 v73, 0, v73
	v_max_f32_e32 v68, 0, v68
	v_max_f32_e32 v69, 0, v69
	v_max_f32_e32 v64, 0, v64
	v_lshl_add_u64 v[98:99], v[96:97], 0, s[22:23]
	v_lshl_add_u64 v[98:99], v[98:99], 0, v[254:255]
	v_max_f32_e32 v90, 0, v90
	v_max_f32_e32 v91, 0, v91
	v_mul_f32_e32 v88, v88, v88
	v_mul_f32_e32 v89, v89, v89
	v_max_f32_e32 v86, 0, v86
	v_max_f32_e32 v87, 0, v87
	v_mul_f32_e32 v84, v84, v84
	v_mul_f32_e32 v85, v85, v85
	v_max_f32_e32 v82, 0, v82
	v_max_f32_e32 v83, 0, v83
	v_mul_f32_e32 v80, v80, v80
	v_mul_f32_e32 v81, v81, v81
	v_max_f32_e32 v78, 0, v78
	v_max_f32_e32 v79, 0, v79
	v_mul_f32_e32 v76, v76, v76
	v_mul_f32_e32 v77, v77, v77
	v_max_f32_e32 v74, 0, v74
	v_max_f32_e32 v75, 0, v75
	v_mul_f32_e32 v72, v72, v72
	v_mul_f32_e32 v73, v73, v73
	v_max_f32_e32 v70, 0, v70
	v_max_f32_e32 v71, 0, v71
	v_mul_f32_e32 v68, v68, v68
	v_mul_f32_e32 v69, v69, v69
	v_max_f32_e32 v65, 0, v65
	v_mul_f32_e32 v64, v64, v64
	v_mul_f32_e32 v90, v90, v90
	v_mul_f32_e32 v91, v91, v91
	v_cvt_pk_bf16_f32 v94, v88, v89
	v_cvt_pk_bf16_f32 v95, v90, v91
	s_nop 1
	v_permlane16_swap_b32_e32 v92, v94
	v_permlane16_swap_b32_e32 v93, v95
	global_store_dwordx4 v[98:99], v[92:95], off
	s_nop 1
	v_mul_f32_e32 v86, v86, v86
	v_mul_f32_e32 v87, v87, v87
	v_cvt_pk_bf16_f32 v84, v84, v85
	v_cvt_pk_bf16_f32 v85, v86, v87
	v_mul_f32_e32 v82, v82, v82
	v_mul_f32_e32 v83, v83, v83
	v_cvt_pk_bf16_f32 v86, v80, v81
	v_cvt_pk_bf16_f32 v87, v82, v83
	s_nop 1
	v_permlane16_swap_b32_e32 v84, v86
	v_permlane16_swap_b32_e32 v85, v87
	global_store_dwordx4 v[98:99], v[84:87], off offset:64
	s_nop 1
	v_mul_f32_e32 v78, v78, v78
	v_mul_f32_e32 v79, v79, v79
	v_cvt_pk_bf16_f32 v76, v76, v77
	v_cvt_pk_bf16_f32 v77, v78, v79
	v_mul_f32_e32 v74, v74, v74
	v_mul_f32_e32 v75, v75, v75
	v_cvt_pk_bf16_f32 v78, v72, v73
	v_cvt_pk_bf16_f32 v79, v74, v75
	s_nop 1
	v_permlane16_swap_b32_e32 v76, v78
	v_permlane16_swap_b32_e32 v77, v79
	global_store_dwordx4 v[98:99], v[76:79], off offset:128
	s_nop 1
	v_mul_f32_e32 v70, v70, v70
	v_mul_f32_e32 v71, v71, v71
	v_cvt_pk_bf16_f32 v68, v68, v69
	v_cvt_pk_bf16_f32 v69, v70, v71
	v_max_f32_e32 v66, 0, v66
	v_max_f32_e32 v67, 0, v67
	v_mul_f32_e32 v65, v65, v65
	v_cvt_pk_bf16_f32 v70, v64, v65
	v_mul_f32_e32 v66, v66, v66
	v_mul_f32_e32 v67, v67, v67
	v_cvt_pk_bf16_f32 v71, v66, v67
	s_nop 1
	v_permlane16_swap_b32_e32 v68, v70
	v_permlane16_swap_b32_e32 v69, v71
	global_store_dwordx4 v[98:99], v[68:71], off offset:192
	s_nop 1
	v_or_b32_e32 v64, 32, v128
	v_ashrrev_i32_e32 v65, 31, v64
	v_mov_b64_e32 v[66:67], v[132:133]
	v_lshlrev_b64 v[64:65], 13, v[64:65]
	v_lshl_add_u64 v[64:65], v[66:67], 0, v[64:65]
	v_lshl_add_u64 v[64:65], v[64:65], 0, v[130:131]
	v_max_f32_e32 v60, 0, v60
	v_max_f32_e32 v61, 0, v61
	v_max_f32_e32 v62, 0, v62
	v_lshl_add_u64 v[64:65], v[64:65], 0, v[134:135]
	v_max_f32_e32 v63, 0, v63
	v_mul_f32_e32 v60, v60, v60
	v_mul_f32_e32 v61, v61, v61
	v_mul_f32_e32 v62, v62, v62
	v_mul_f32_e32 v63, v63, v63
	v_cvt_pk_bf16_f32 v60, v60, v61
	v_cvt_pk_bf16_f32 v61, v62, v63
	v_max_f32_e32 v56, 0, v56
	v_max_f32_e32 v57, 0, v57
	v_max_f32_e32 v52, 0, v52
	v_max_f32_e32 v53, 0, v53
	v_max_f32_e32 v48, 0, v48
	v_max_f32_e32 v49, 0, v49
	v_max_f32_e32 v44, 0, v44
	v_max_f32_e32 v45, 0, v45
	v_max_f32_e32 v40, 0, v40
	v_max_f32_e32 v41, 0, v41
	v_max_f32_e32 v36, 0, v36
	v_max_f32_e32 v37, 0, v37
	v_max_f32_e32 v32, 0, v32
	v_lshl_add_u64 v[66:67], v[64:65], 0, s[22:23]
	v_lshl_add_u64 v[66:67], v[66:67], 0, v[254:255]
	v_max_f32_e32 v58, 0, v58
	v_max_f32_e32 v59, 0, v59
	v_mul_f32_e32 v56, v56, v56
	v_mul_f32_e32 v57, v57, v57
	v_max_f32_e32 v54, 0, v54
	v_max_f32_e32 v55, 0, v55
	v_mul_f32_e32 v52, v52, v52
	v_mul_f32_e32 v53, v53, v53
	v_max_f32_e32 v50, 0, v50
	v_max_f32_e32 v51, 0, v51
	v_mul_f32_e32 v48, v48, v48
	v_mul_f32_e32 v49, v49, v49
	v_max_f32_e32 v46, 0, v46
	v_max_f32_e32 v47, 0, v47
	v_mul_f32_e32 v44, v44, v44
	v_mul_f32_e32 v45, v45, v45
	v_max_f32_e32 v42, 0, v42
	v_max_f32_e32 v43, 0, v43
	v_mul_f32_e32 v40, v40, v40
	v_mul_f32_e32 v41, v41, v41
	v_max_f32_e32 v38, 0, v38
	v_max_f32_e32 v39, 0, v39
	v_mul_f32_e32 v36, v36, v36
	v_mul_f32_e32 v37, v37, v37
	v_max_f32_e32 v33, 0, v33
	v_mul_f32_e32 v32, v32, v32
	v_mul_f32_e32 v58, v58, v58
	v_mul_f32_e32 v59, v59, v59
	v_cvt_pk_bf16_f32 v62, v56, v57
	v_cvt_pk_bf16_f32 v63, v58, v59
	s_nop 1
	v_permlane16_swap_b32_e32 v60, v62
	v_permlane16_swap_b32_e32 v61, v63
	global_store_dwordx4 v[66:67], v[60:63], off
	s_nop 1
	v_mul_f32_e32 v54, v54, v54
	v_mul_f32_e32 v55, v55, v55
	v_cvt_pk_bf16_f32 v52, v52, v53
	v_cvt_pk_bf16_f32 v53, v54, v55
	v_mul_f32_e32 v50, v50, v50
	v_mul_f32_e32 v51, v51, v51
	v_cvt_pk_bf16_f32 v54, v48, v49
	v_cvt_pk_bf16_f32 v55, v50, v51
	s_nop 1
	v_permlane16_swap_b32_e32 v52, v54
	v_permlane16_swap_b32_e32 v53, v55
	global_store_dwordx4 v[66:67], v[52:55], off offset:64
	s_nop 1
	v_mul_f32_e32 v46, v46, v46
	v_mul_f32_e32 v47, v47, v47
	v_cvt_pk_bf16_f32 v44, v44, v45
	v_cvt_pk_bf16_f32 v45, v46, v47
	v_mul_f32_e32 v42, v42, v42
	v_mul_f32_e32 v43, v43, v43
	v_cvt_pk_bf16_f32 v46, v40, v41
	v_cvt_pk_bf16_f32 v47, v42, v43
	s_nop 1
	v_permlane16_swap_b32_e32 v44, v46
	v_permlane16_swap_b32_e32 v45, v47
	global_store_dwordx4 v[66:67], v[44:47], off offset:128
	s_nop 1
	v_mul_f32_e32 v38, v38, v38
	v_mul_f32_e32 v39, v39, v39
	v_cvt_pk_bf16_f32 v36, v36, v37
	v_cvt_pk_bf16_f32 v37, v38, v39
	v_max_f32_e32 v34, 0, v34
	v_max_f32_e32 v35, 0, v35
	v_mul_f32_e32 v33, v33, v33
	v_cvt_pk_bf16_f32 v38, v32, v33
	v_mul_f32_e32 v34, v34, v34
	v_mul_f32_e32 v35, v35, v35
	v_cvt_pk_bf16_f32 v39, v34, v35
	s_nop 1
	v_permlane16_swap_b32_e32 v36, v38
	v_permlane16_swap_b32_e32 v37, v39
	global_store_dwordx4 v[66:67], v[36:39], off offset:192
	s_nop 1
	v_or_b32_e32 v32, 48, v128
	v_ashrrev_i32_e32 v33, 31, v32
	v_mov_b64_e32 v[34:35], v[132:133]
	v_lshlrev_b64 v[32:33], 13, v[32:33]
	v_lshl_add_u64 v[32:33], v[34:35], 0, v[32:33]
	v_lshl_add_u64 v[32:33], v[32:33], 0, v[130:131]
	v_max_f32_e32 v28, 0, v28
	v_max_f32_e32 v29, 0, v29
	v_max_f32_e32 v30, 0, v30
	v_lshl_add_u64 v[32:33], v[32:33], 0, v[134:135]
	v_max_f32_e32 v31, 0, v31
	v_mul_f32_e32 v28, v28, v28
	v_mul_f32_e32 v29, v29, v29
	v_mul_f32_e32 v30, v30, v30
	v_mul_f32_e32 v31, v31, v31
	v_cvt_pk_bf16_f32 v28, v28, v29
	v_cvt_pk_bf16_f32 v29, v30, v31
	v_max_f32_e32 v24, 0, v24
	v_max_f32_e32 v25, 0, v25
	v_max_f32_e32 v20, 0, v20
	v_max_f32_e32 v21, 0, v21
	v_max_f32_e32 v16, 0, v16
	v_max_f32_e32 v17, 0, v17
	v_max_f32_e32 v12, 0, v12
	v_max_f32_e32 v13, 0, v13
	v_max_f32_e32 v8, 0, v8
	v_max_f32_e32 v9, 0, v9
	v_max_f32_e32 v4, 0, v4
	v_max_f32_e32 v5, 0, v5
	v_max_f32_e32 v0, 0, v0
	v_max_f32_e32 v1, 0, v1
	v_lshl_add_u64 v[34:35], v[32:33], 0, s[22:23]
	v_lshl_add_u64 v[34:35], v[34:35], 0, v[254:255]
	v_max_f32_e32 v26, 0, v26
	v_max_f32_e32 v27, 0, v27
	v_mul_f32_e32 v24, v24, v24
	v_mul_f32_e32 v25, v25, v25
	v_max_f32_e32 v22, 0, v22
	v_max_f32_e32 v23, 0, v23
	v_mul_f32_e32 v20, v20, v20
	v_mul_f32_e32 v21, v21, v21
	v_max_f32_e32 v18, 0, v18
	v_max_f32_e32 v19, 0, v19
	v_mul_f32_e32 v16, v16, v16
	v_mul_f32_e32 v17, v17, v17
	v_max_f32_e32 v14, 0, v14
	v_max_f32_e32 v15, 0, v15
	v_mul_f32_e32 v12, v12, v12
	v_mul_f32_e32 v13, v13, v13
	v_max_f32_e32 v10, 0, v10
	v_max_f32_e32 v11, 0, v11
	v_mul_f32_e32 v8, v8, v8
	v_mul_f32_e32 v9, v9, v9
	v_max_f32_e32 v6, 0, v6
	v_max_f32_e32 v7, 0, v7
	v_mul_f32_e32 v4, v4, v4
	v_mul_f32_e32 v5, v5, v5
	v_max_f32_e32 v2, 0, v2
	v_max_f32_e32 v3, 0, v3
	v_mul_f32_e32 v0, v0, v0
	v_mul_f32_e32 v1, v1, v1
	s_add_i32 s15, s15, 1
	s_mov_b64 s[4:5], 0
	v_mul_f32_e32 v26, v26, v26
	v_mul_f32_e32 v27, v27, v27
	v_cvt_pk_bf16_f32 v30, v24, v25
	v_cvt_pk_bf16_f32 v31, v26, v27
	s_nop 1
	v_permlane16_swap_b32_e32 v28, v30
	v_permlane16_swap_b32_e32 v29, v31
	global_store_dwordx4 v[34:35], v[28:31], off
	s_nop 1
	v_mul_f32_e32 v22, v22, v22
	v_mul_f32_e32 v23, v23, v23
	v_cvt_pk_bf16_f32 v20, v20, v21
	v_cvt_pk_bf16_f32 v21, v22, v23
	v_mul_f32_e32 v18, v18, v18
	v_mul_f32_e32 v19, v19, v19
	v_cvt_pk_bf16_f32 v22, v16, v17
	v_cvt_pk_bf16_f32 v23, v18, v19
	s_nop 1
	v_permlane16_swap_b32_e32 v20, v22
	v_permlane16_swap_b32_e32 v21, v23
	global_store_dwordx4 v[34:35], v[20:23], off offset:64
	s_nop 1
	v_mul_f32_e32 v14, v14, v14
	v_mul_f32_e32 v15, v15, v15
	v_cvt_pk_bf16_f32 v12, v12, v13
	v_cvt_pk_bf16_f32 v13, v14, v15
	v_mul_f32_e32 v10, v10, v10
	v_mul_f32_e32 v11, v11, v11
	v_cvt_pk_bf16_f32 v14, v8, v9
	v_cvt_pk_bf16_f32 v15, v10, v11
	s_nop 1
	v_permlane16_swap_b32_e32 v12, v14
	v_permlane16_swap_b32_e32 v13, v15
	global_store_dwordx4 v[34:35], v[12:15], off offset:128
	s_nop 1
	v_mul_f32_e32 v6, v6, v6
	v_mul_f32_e32 v7, v7, v7
	v_cvt_pk_bf16_f32 v4, v4, v5
	v_cvt_pk_bf16_f32 v5, v6, v7
	v_mul_f32_e32 v2, v2, v2
	v_mul_f32_e32 v3, v3, v3
	v_cvt_pk_bf16_f32 v6, v0, v1
	v_cvt_pk_bf16_f32 v7, v2, v3
	s_nop 1
	v_permlane16_swap_b32_e32 v4, v6
	v_permlane16_swap_b32_e32 v5, v7
	global_store_dwordx4 v[34:35], v[4:7], off offset:192
	s_nop 1
